# v36 + static priority raise (s_setprio 1) for the leading wave half during every epilogue, reset at epilogue end
# speedup vs baseline: 1.0036x; 1.0036x over previous
.LBB0_259:
	s_cmp_eq_u32 s91, s100
	s_cbranch_scc0 .Lcr0_slow
	s_and_b64 vcc, exec, s[16:17]
	s_cbranch_vccz .Lcr0_261
	s_barrier
	s_setprio 1

.Lcr0_slow:
	s_mov_b32 s100, s91
	s_and_b64 vcc, exec, s[16:17]
	s_cbranch_vccz .LBB0_261
	s_barrier
	s_setprio 1

.LBB0_293:
	s_setprio 0
	s_add_u32 s6, s93, 0xfffe0000
	s_addc_u32 s7, s94, -1
	s_andn2_b64 vcc, exec, s[26:27]
	s_cbranch_vccnz .LBB0_297
	s_andn2_b64 vcc, exec, s[14:15]
	v_readlane_b32 s94, v248, 14
	s_cbranch_vccnz .LBB0_296
	s_barrier

.LBB0_368:
	s_and_b64 vcc, exec, s[28:29]
	s_cbranch_vccz .LBB0_370
	s_barrier
	s_setprio 1

.LBB0_480:
	s_setprio 0
	s_or_b64 exec, exec, s[50:51]
	s_and_b64 vcc, exec, s[10:11]
	s_mov_b32 s26, s95
	s_cbranch_vccnz .LBB0_484
	s_andn2_b64 vcc, exec, s[24:25]
	s_cbranch_vccnz .LBB0_483
	s_barrier

.LBB0_519:
	ds_read_b128 v[130:133], v141
	ds_read_b128 v[134:137], v141 offset:1024
	ds_read_b128 v[146:149], v141 offset:2048
	ds_read_b128 v[150:153], v141 offset:3072
	ds_read_b128 v[154:157], v142
	ds_read_b128 v[158:161], v142 offset:1024
	ds_read_b128 v[162:165], v142 offset:2048
	ds_read_b128 v[166:169], v142 offset:3072
	s_add_u32 s24, s26, 0x10000
	s_addc_u32 s25, s27, 0
	s_cmp_eq_u32 s77, 12
	s_cselect_b32 s48, s17, s24
	s_cselect_b32 s49, s1, s25
	s_cselect_b32 s30, s23, s75
	s_cselect_b32 s31, s15, s76
	s_add_u32 s28, s48, 0x8000
	s_addc_u32 s29, s49, 0
	ds_read_b128 v[170:173], v143
	ds_read_b128 v[174:177], v143 offset:1024
	ds_read_b128 v[178:181], v143 offset:2048
	ds_read_b128 v[182:185], v143 offset:3072
	ds_read_b128 v[186:189], v143 offset:4096
	ds_read_b128 v[190:193], v143 offset:5120
	ds_read_b128 v[198:201], v143 offset:6144
	ds_read_b128 v[202:205], v143 offset:7168
	s_add_u32 s38, s30, 0x8000
	s_addc_u32 s39, s31, 0
	s_add_u32 s26, s26, 0xc000
	s_addc_u32 s27, s27, 0
	s_mov_b32 m0, s72
	s_nop 0
	global_load_lds_dwordx4 v195, s[26:27]
	s_add_u32 m0, s72, 0x2000
	s_nop 0
	global_load_lds_dwordx4 v212, s[26:27]
	s_waitcnt vmcnt(8)
	s_waitcnt lgkmcnt(0)
	s_setprio 1
	s_barrier
	v_mfma_f32_16x16x32_bf16 v[122:125], v[130:133], v[170:173], v[122:125]
	v_mfma_f32_16x16x32_bf16 v[126:129], v[146:149], v[170:173], v[126:129]
	s_waitcnt lgkmcnt(5)
	v_mfma_f32_16x16x32_bf16 v[110:113], v[130:133], v[178:181], v[110:113]
	v_mfma_f32_16x16x32_bf16 v[106:109], v[146:149], v[178:181], v[106:109]
	s_waitcnt lgkmcnt(3)
	v_mfma_f32_16x16x32_bf16 v[94:97], v[130:133], v[186:189], v[94:97]
	v_mfma_f32_16x16x32_bf16 v[90:93], v[146:149], v[186:189], v[90:93]
	s_waitcnt lgkmcnt(1)
	v_mfma_f32_16x16x32_bf16 v[78:81], v[130:133], v[198:201], v[78:81]
	v_mfma_f32_16x16x32_bf16 v[74:77], v[146:149], v[198:201], v[74:77]
	v_mfma_f32_16x16x32_bf16 v[122:125], v[134:137], v[174:177], v[122:125]
	v_mfma_f32_16x16x32_bf16 v[126:129], v[150:153], v[174:177], v[126:129]
	v_mfma_f32_16x16x32_bf16 v[110:113], v[134:137], v[182:185], v[110:113]
	v_mfma_f32_16x16x32_bf16 v[106:109], v[150:153], v[182:185], v[106:109]
	v_mfma_f32_16x16x32_bf16 v[94:97], v[134:137], v[190:193], v[94:97]
	v_mfma_f32_16x16x32_bf16 v[90:93], v[150:153], v[190:193], v[90:93]
	s_waitcnt lgkmcnt(0)
	v_mfma_f32_16x16x32_bf16 v[78:81], v[134:137], v[202:205], v[78:81]
	v_mfma_f32_16x16x32_bf16 v[74:77], v[150:153], v[202:205], v[74:77]
	s_setprio 0
	s_setprio 1
	v_mfma_f32_16x16x32_bf16 v[114:117], v[154:157], v[170:173], v[114:117]
	v_mfma_f32_16x16x32_bf16 v[118:121], v[162:165], v[170:173], v[118:121]
	v_mfma_f32_16x16x32_bf16 v[98:101], v[154:157], v[178:181], v[98:101]
	v_mfma_f32_16x16x32_bf16 v[102:105], v[162:165], v[178:181], v[102:105]
	v_mfma_f32_16x16x32_bf16 v[82:85], v[154:157], v[186:189], v[82:85]
	v_mfma_f32_16x16x32_bf16 v[86:89], v[162:165], v[186:189], v[86:89]
	v_mfma_f32_16x16x32_bf16 v[66:69], v[154:157], v[198:201], v[66:69]
	v_mfma_f32_16x16x32_bf16 v[70:73], v[162:165], v[198:201], v[70:73]
	v_mfma_f32_16x16x32_bf16 v[114:117], v[158:161], v[174:177], v[114:117]
	v_mfma_f32_16x16x32_bf16 v[118:121], v[166:169], v[174:177], v[118:121]
	v_mfma_f32_16x16x32_bf16 v[98:101], v[158:161], v[182:185], v[98:101]
	v_mfma_f32_16x16x32_bf16 v[102:105], v[166:169], v[182:185], v[102:105]
	v_mfma_f32_16x16x32_bf16 v[82:85], v[158:161], v[190:193], v[82:85]
	v_mfma_f32_16x16x32_bf16 v[86:89], v[166:169], v[190:193], v[86:89]
	s_setprio 2
	s_barrier
	v_mfma_f32_16x16x32_bf16 v[66:69], v[158:161], v[202:205], v[66:69]
	v_mfma_f32_16x16x32_bf16 v[70:73], v[166:169], v[202:205], v[70:73]
	s_setprio 0
	s_nop 0
	ds_read_b128 v[170:173], v143 offset:16384
	ds_read_b128 v[174:177], v143 offset:17408
	ds_read_b128 v[178:181], v143 offset:18432
	ds_read_b128 v[182:185], v143 offset:19456
	ds_read_b128 v[186:189], v143 offset:20480
	ds_read_b128 v[190:193], v143 offset:21504
	ds_read_b128 v[198:201], v143 offset:22528
	ds_read_b128 v[202:205], v143 offset:23552
	s_mov_b32 m0, s55
	s_nop 0
	global_load_lds_dwordx4 v195, s[30:31]
	s_add_u32 m0, s55, 0x2000
	s_nop 0
	global_load_lds_dwordx4 v212, s[30:31]
	s_add_u32 s26, s30, 0x4000
	s_addc_u32 s27, s31, 0
	s_mov_b32 m0, s62
	s_nop 0
	global_load_lds_dwordx4 v195, s[26:27]
	s_add_u32 m0, s62, 0x2000
	s_nop 0
	global_load_lds_dwordx4 v212, s[26:27]
	s_nop 0
	s_mov_b32 m0, s54
	s_nop 0
	global_load_lds_dwordx4 v195, s[48:49]
	s_add_u32 m0, s54, 0x2000
	s_nop 0
	global_load_lds_dwordx4 v212, s[48:49]
	s_waitcnt vmcnt(8)
	s_waitcnt lgkmcnt(0)
	s_setprio 1
	s_barrier
	v_mfma_f32_16x16x32_bf16 v[62:65], v[130:133], v[170:173], v[62:65]
	v_mfma_f32_16x16x32_bf16 v[58:61], v[146:149], v[170:173], v[58:61]
	s_waitcnt lgkmcnt(5)
	v_mfma_f32_16x16x32_bf16 v[46:49], v[130:133], v[178:181], v[46:49]
	v_mfma_f32_16x16x32_bf16 v[42:45], v[146:149], v[178:181], v[42:45]
	s_waitcnt lgkmcnt(3)
	v_mfma_f32_16x16x32_bf16 v[30:33], v[130:133], v[186:189], v[30:33]
	v_mfma_f32_16x16x32_bf16 v[26:29], v[146:149], v[186:189], v[26:29]
	s_waitcnt lgkmcnt(1)
	v_mfma_f32_16x16x32_bf16 v[14:17], v[130:133], v[198:201], v[14:17]
	v_mfma_f32_16x16x32_bf16 v[10:13], v[146:149], v[198:201], v[10:13]
	v_mfma_f32_16x16x32_bf16 v[62:65], v[134:137], v[174:177], v[62:65]
	v_mfma_f32_16x16x32_bf16 v[58:61], v[150:153], v[174:177], v[58:61]
	v_mfma_f32_16x16x32_bf16 v[46:49], v[134:137], v[182:185], v[46:49]
	v_mfma_f32_16x16x32_bf16 v[42:45], v[150:153], v[182:185], v[42:45]
	v_mfma_f32_16x16x32_bf16 v[30:33], v[134:137], v[190:193], v[30:33]
	v_mfma_f32_16x16x32_bf16 v[26:29], v[150:153], v[190:193], v[26:29]
	s_waitcnt lgkmcnt(0)
	v_mfma_f32_16x16x32_bf16 v[14:17], v[134:137], v[202:205], v[14:17]
	v_mfma_f32_16x16x32_bf16 v[10:13], v[150:153], v[202:205], v[10:13]
	s_setprio 0
	s_setprio 1
	v_mfma_f32_16x16x32_bf16 v[50:53], v[154:157], v[170:173], v[50:53]
	v_mfma_f32_16x16x32_bf16 v[54:57], v[162:165], v[170:173], v[54:57]
	v_mfma_f32_16x16x32_bf16 v[34:37], v[154:157], v[178:181], v[34:37]
	v_mfma_f32_16x16x32_bf16 v[38:41], v[162:165], v[178:181], v[38:41]
	v_mfma_f32_16x16x32_bf16 v[18:21], v[154:157], v[186:189], v[18:21]
	v_mfma_f32_16x16x32_bf16 v[22:25], v[162:165], v[186:189], v[22:25]
	v_mfma_f32_16x16x32_bf16 v[2:5], v[154:157], v[198:201], v[2:5]
	v_mfma_f32_16x16x32_bf16 v[6:9], v[162:165], v[198:201], v[6:9]
	v_mfma_f32_16x16x32_bf16 v[50:53], v[158:161], v[174:177], v[50:53]
	v_mfma_f32_16x16x32_bf16 v[54:57], v[166:169], v[174:177], v[54:57]
	v_mfma_f32_16x16x32_bf16 v[34:37], v[158:161], v[182:185], v[34:37]
	v_mfma_f32_16x16x32_bf16 v[38:41], v[166:169], v[182:185], v[38:41]
	v_mfma_f32_16x16x32_bf16 v[18:21], v[158:161], v[190:193], v[18:21]
	v_mfma_f32_16x16x32_bf16 v[22:25], v[166:169], v[190:193], v[22:25]
	s_setprio 2
	s_barrier
	v_mfma_f32_16x16x32_bf16 v[2:5], v[158:161], v[202:205], v[2:5]
	v_mfma_f32_16x16x32_bf16 v[6:9], v[166:169], v[202:205], v[6:9]
	s_setprio 0
	s_nop 0
	ds_read_b128 v[130:133], v144
	ds_read_b128 v[134:137], v144 offset:1024
	ds_read_b128 v[146:149], v144 offset:2048
	ds_read_b128 v[150:153], v144 offset:3072
	ds_read_b128 v[154:157], v145
	ds_read_b128 v[158:161], v145 offset:1024
	ds_read_b128 v[162:165], v145 offset:2048
	ds_read_b128 v[166:169], v145 offset:3072
	ds_read_b128 v[170:173], v143 offset:32768
	ds_read_b128 v[174:177], v143 offset:33792
	ds_read_b128 v[178:181], v143 offset:34816
	ds_read_b128 v[182:185], v143 offset:35840
	ds_read_b128 v[186:189], v143 offset:36864
	ds_read_b128 v[190:193], v143 offset:37888
	ds_read_b128 v[198:201], v143 offset:38912
	ds_read_b128 v[202:205], v143 offset:39936
	s_add_u32 s26, s48, 0x4000
	s_addc_u32 s27, s49, 0
	s_mov_b32 m0, s63
	s_nop 0
	global_load_lds_dwordx4 v195, s[26:27]
	s_add_u32 m0, s63, 0x2000
	s_nop 0
	global_load_lds_dwordx4 v212, s[26:27]
	s_waitcnt vmcnt(8)
	s_waitcnt lgkmcnt(0)
	s_setprio 1
	s_barrier
	v_mfma_f32_16x16x32_bf16 v[122:125], v[130:133], v[170:173], v[122:125]
	v_mfma_f32_16x16x32_bf16 v[126:129], v[146:149], v[170:173], v[126:129]
	s_waitcnt lgkmcnt(5)
	v_mfma_f32_16x16x32_bf16 v[110:113], v[130:133], v[178:181], v[110:113]
	v_mfma_f32_16x16x32_bf16 v[106:109], v[146:149], v[178:181], v[106:109]
	s_waitcnt lgkmcnt(3)
	v_mfma_f32_16x16x32_bf16 v[94:97], v[130:133], v[186:189], v[94:97]
	v_mfma_f32_16x16x32_bf16 v[90:93], v[146:149], v[186:189], v[90:93]
	s_waitcnt lgkmcnt(1)
	v_mfma_f32_16x16x32_bf16 v[78:81], v[130:133], v[198:201], v[78:81]
	v_mfma_f32_16x16x32_bf16 v[74:77], v[146:149], v[198:201], v[74:77]
	v_mfma_f32_16x16x32_bf16 v[122:125], v[134:137], v[174:177], v[122:125]
	v_mfma_f32_16x16x32_bf16 v[126:129], v[150:153], v[174:177], v[126:129]
	v_mfma_f32_16x16x32_bf16 v[110:113], v[134:137], v[182:185], v[110:113]
	v_mfma_f32_16x16x32_bf16 v[106:109], v[150:153], v[182:185], v[106:109]
	v_mfma_f32_16x16x32_bf16 v[94:97], v[134:137], v[190:193], v[94:97]
	v_mfma_f32_16x16x32_bf16 v[90:93], v[150:153], v[190:193], v[90:93]
	s_waitcnt lgkmcnt(0)
	v_mfma_f32_16x16x32_bf16 v[78:81], v[134:137], v[202:205], v[78:81]
	v_mfma_f32_16x16x32_bf16 v[74:77], v[150:153], v[202:205], v[74:77]
	s_setprio 0
	s_setprio 1
	v_mfma_f32_16x16x32_bf16 v[114:117], v[154:157], v[170:173], v[114:117]
	v_mfma_f32_16x16x32_bf16 v[118:121], v[162:165], v[170:173], v[118:121]
	v_mfma_f32_16x16x32_bf16 v[98:101], v[154:157], v[178:181], v[98:101]
	v_mfma_f32_16x16x32_bf16 v[102:105], v[162:165], v[178:181], v[102:105]
	v_mfma_f32_16x16x32_bf16 v[82:85], v[154:157], v[186:189], v[82:85]
	v_mfma_f32_16x16x32_bf16 v[86:89], v[162:165], v[186:189], v[86:89]
	v_mfma_f32_16x16x32_bf16 v[66:69], v[154:157], v[198:201], v[66:69]
	v_mfma_f32_16x16x32_bf16 v[70:73], v[162:165], v[198:201], v[70:73]
	v_mfma_f32_16x16x32_bf16 v[114:117], v[158:161], v[174:177], v[114:117]
	v_mfma_f32_16x16x32_bf16 v[118:121], v[166:169], v[174:177], v[118:121]
	v_mfma_f32_16x16x32_bf16 v[98:101], v[158:161], v[182:185], v[98:101]
	v_mfma_f32_16x16x32_bf16 v[102:105], v[166:169], v[182:185], v[102:105]
	v_mfma_f32_16x16x32_bf16 v[82:85], v[158:161], v[190:193], v[82:85]
	v_mfma_f32_16x16x32_bf16 v[86:89], v[166:169], v[190:193], v[86:89]
	s_setprio 2
	s_barrier
	v_mfma_f32_16x16x32_bf16 v[66:69], v[158:161], v[202:205], v[66:69]
	v_mfma_f32_16x16x32_bf16 v[70:73], v[166:169], v[202:205], v[70:73]
	s_setprio 0
	s_nop 0
	ds_read_b128 v[170:173], v143 offset:49152
	ds_read_b128 v[174:177], v143 offset:50176
	ds_read_b128 v[178:181], v143 offset:51200
	ds_read_b128 v[182:185], v143 offset:52224
	ds_read_b128 v[186:189], v143 offset:53248
	ds_read_b128 v[190:193], v143 offset:54272
	ds_read_b128 v[198:201], v143 offset:55296
	ds_read_b128 v[202:205], v143 offset:56320
	s_mov_b32 m0, s69
	s_nop 0
	global_load_lds_dwordx4 v195, s[38:39]
	s_add_u32 m0, s69, 0x2000
	s_nop 0
	global_load_lds_dwordx4 v212, s[38:39]
	s_add_u32 s26, s30, 0xc000
	s_addc_u32 s27, s31, 0
	s_mov_b32 m0, s71
	s_nop 0
	global_load_lds_dwordx4 v195, s[26:27]
	s_add_u32 m0, s71, 0x2000
	s_nop 0
	global_load_lds_dwordx4 v212, s[26:27]
	s_nop 0
	s_mov_b32 m0, s70
	s_nop 0
	global_load_lds_dwordx4 v195, s[28:29]
	s_add_u32 m0, s70, 0x2000
	s_nop 0
	global_load_lds_dwordx4 v212, s[28:29]
	s_waitcnt vmcnt(8)
	s_waitcnt lgkmcnt(0)
	s_setprio 1
	s_barrier
	v_mfma_f32_16x16x32_bf16 v[62:65], v[130:133], v[170:173], v[62:65]
	v_mfma_f32_16x16x32_bf16 v[58:61], v[146:149], v[170:173], v[58:61]
	s_waitcnt lgkmcnt(5)
	v_mfma_f32_16x16x32_bf16 v[46:49], v[130:133], v[178:181], v[46:49]
	v_mfma_f32_16x16x32_bf16 v[42:45], v[146:149], v[178:181], v[42:45]
	s_waitcnt lgkmcnt(3)
	v_mfma_f32_16x16x32_bf16 v[30:33], v[130:133], v[186:189], v[30:33]
	v_mfma_f32_16x16x32_bf16 v[26:29], v[146:149], v[186:189], v[26:29]
	s_waitcnt lgkmcnt(1)
	v_mfma_f32_16x16x32_bf16 v[14:17], v[130:133], v[198:201], v[14:17]
	v_mfma_f32_16x16x32_bf16 v[10:13], v[146:149], v[198:201], v[10:13]
	v_mfma_f32_16x16x32_bf16 v[62:65], v[134:137], v[174:177], v[62:65]
	v_mfma_f32_16x16x32_bf16 v[58:61], v[150:153], v[174:177], v[58:61]
	v_mfma_f32_16x16x32_bf16 v[46:49], v[134:137], v[182:185], v[46:49]
	v_mfma_f32_16x16x32_bf16 v[42:45], v[150:153], v[182:185], v[42:45]
	v_mfma_f32_16x16x32_bf16 v[30:33], v[134:137], v[190:193], v[30:33]
	v_mfma_f32_16x16x32_bf16 v[26:29], v[150:153], v[190:193], v[26:29]
	s_waitcnt lgkmcnt(0)
	v_mfma_f32_16x16x32_bf16 v[14:17], v[134:137], v[202:205], v[14:17]
	v_mfma_f32_16x16x32_bf16 v[10:13], v[150:153], v[202:205], v[10:13]
	s_setprio 0
	s_setprio 1
	v_mfma_f32_16x16x32_bf16 v[50:53], v[154:157], v[170:173], v[50:53]
	v_mfma_f32_16x16x32_bf16 v[54:57], v[162:165], v[170:173], v[54:57]
	v_mfma_f32_16x16x32_bf16 v[34:37], v[154:157], v[178:181], v[34:37]
	v_mfma_f32_16x16x32_bf16 v[38:41], v[162:165], v[178:181], v[38:41]
	v_mfma_f32_16x16x32_bf16 v[18:21], v[154:157], v[186:189], v[18:21]
	v_mfma_f32_16x16x32_bf16 v[22:25], v[162:165], v[186:189], v[22:25]
	v_mfma_f32_16x16x32_bf16 v[2:5], v[154:157], v[198:201], v[2:5]
	v_mfma_f32_16x16x32_bf16 v[6:9], v[162:165], v[198:201], v[6:9]
	v_mfma_f32_16x16x32_bf16 v[50:53], v[158:161], v[174:177], v[50:53]
	v_mfma_f32_16x16x32_bf16 v[54:57], v[166:169], v[174:177], v[54:57]
	v_mfma_f32_16x16x32_bf16 v[34:37], v[158:161], v[182:185], v[34:37]
	v_mfma_f32_16x16x32_bf16 v[38:41], v[166:169], v[182:185], v[38:41]
	v_mfma_f32_16x16x32_bf16 v[18:21], v[158:161], v[190:193], v[18:21]
	v_mfma_f32_16x16x32_bf16 v[22:25], v[166:169], v[190:193], v[22:25]
	s_setprio 2
	s_barrier
	v_mfma_f32_16x16x32_bf16 v[2:5], v[158:161], v[202:205], v[2:5]
	v_mfma_f32_16x16x32_bf16 v[6:9], v[166:169], v[202:205], v[6:9]
	s_setprio 0
	s_nop 0
	s_add_i32 s77, s77, 2
	s_add_u32 s75, s75, 0x10000
	s_addc_u32 s76, s76, 0
	s_cmp_gt_u32 s77, 13
	s_mov_b64 s[26:27], s[24:25]
	s_cbranch_scc0 .LBB0_519
	s_and_b64 vcc, exec, s[10:11]
	s_cbranch_vccz .LBB0_522
	s_barrier
	s_setprio 1

.LBB0_559:
	s_setprio 0
	s_waitcnt vmcnt(0)
	s_barrier

.LBB0_639:
	s_and_b64 vcc, exec, s[96:97]
	s_cbranch_vccz .LBB0_641
	s_barrier
	s_setprio 1

.LBB0_828:
	s_setprio 0
	s_andn2_b64 vcc, exec, s[20:21]
	s_cbranch_vccnz .LBB0_598
	s_andn2_b64 vcc, exec, s[56:57]
	s_cbranch_vccnz .LBB0_597
	s_barrier
	s_branch .LBB0_597

.LBB0_1070:
	s_and_b64 vcc, exec, s[74:75]
	s_cbranch_vccz .LBB0_1072
	s_barrier
	s_setprio 1

.LBB0_1259:
	s_setprio 0
	s_add_u32 s0, s94, 0xfffe0000
	s_addc_u32 s1, s96, -1
	s_andn2_b64 vcc, exec, s[48:49]
	s_cbranch_vccnz .LBB0_1263
	s_andn2_b64 vcc, exec, s[18:19]
	v_readlane_b32 s94, v248, 14
	s_cbranch_vccnz .LBB0_1262
	s_barrier

.LBB0_1340:
	s_and_b64 vcc, exec, s[20:21]
	s_cbranch_vccz .LBB0_1342
	s_barrier
	s_setprio 1

.LBB0_1345:
	s_setprio 0
	s_waitcnt vmcnt(0)
	v_readlane_b32 s56, v248, 17
	v_readlane_b32 s57, v248, 18
	s_barrier

.LBB0_1442:
	s_setprio 0
	s_add_u32 s6, s71, 0xfffe0000
	s_addc_u32 s7, s72, -1
	s_andn2_b64 vcc, exec, s[22:23]
	s_cbranch_vccnz .LBB0_1446
	s_andn2_b64 vcc, exec, s[18:19]
	s_cbranch_vccnz .LBB0_1445
	s_barrier

.LBB0_1635:
	s_setprio 0
	s_or_b64 exec, exec, s[50:51]
	s_andn2_b64 vcc, exec, s[48:49]
	s_mov_b32 s10, s82
	s_cbranch_vccnz .LBB0_1639
	s_andn2_b64 vcc, exec, s[24:25]
	s_cbranch_vccnz .LBB0_1638
	s_barrier

.LBB0_1716:
	s_and_b64 vcc, exec, s[22:23]
	s_cbranch_vccz .LBB0_1718
	s_barrier
	s_setprio 1

.LBB0_2034:
	s_setprio 0
	s_or_b64 exec, exec, s[42:43]
	s_add_u32 s6, s75, 0xfffe0000
	s_addc_u32 s7, s76, -1
	s_andn2_b64 vcc, exec, s[24:25]
	s_cbranch_vccnz .LBB0_2038
	s_andn2_b64 vcc, exec, s[18:19]
	s_cbranch_vccnz .LBB0_2037
	s_barrier

.LBB0_2124:
	s_cmp_eq_u32 s82, s100
	s_cbranch_scc0 .Lcr1_slow
	s_and_b64 vcc, exec, s[24:25]
	s_cbranch_vccz .Lcr1_2126
	s_barrier
	s_setprio 1

.Lcr1_slow:
	s_mov_b32 s100, s82
	s_and_b64 vcc, exec, s[24:25]
	s_cbranch_vccz .LBB0_2126
	s_barrier
	s_setprio 1

.LBB0_2158:
	s_setprio 0
	s_andn2_b64 vcc, exec, s[48:49]
	s_mov_b32 s10, s82
	s_cbranch_vccnz .LBB0_2162
	s_andn2_b64 vcc, exec, s[22:23]
	s_cbranch_vccnz .LBB0_2161
	s_barrier

.LBB0_2233:
	s_and_b64 vcc, exec, s[24:25]
	s_cbranch_vccz .LBB0_2235
	s_barrier
	s_setprio 1

.LBB0_2345:
	s_setprio 0
	s_or_b64 exec, exec, s[38:39]
	s_and_b64 vcc, exec, s[10:11]
	s_mov_b32 s10, s74
	s_cbranch_vccnz .LBB0_2349
	s_andn2_b64 vcc, exec, s[20:21]
	s_cbranch_vccnz .LBB0_2348
	s_barrier
